# D epilogue v4: rs folded into sigmoid denominator (K/rs per row) so up*rs mul only for m=0 rows
# speedup vs baseline: 1.0072x; 1.0072x over previous
.Ldepi_rs_cached:
	v_rcp_f32_e32 v170, v244
	v_rcp_f32_e32 v171, v245
	v_rcp_f32_e32 v172, v246
	v_rcp_f32_e32 v173, v247
	v_rcp_f32_e32 v169, v248
	v_rcp_f32_e32 v177, v249
	v_rcp_f32_e32 v191, v250
	v_rcp_f32_e32 v199, v251
	v_mul_f32_e32 v170, s101, v170
	v_mul_f32_e32 v171, s101, v171
	v_mul_f32_e32 v172, s101, v172
	v_mul_f32_e32 v173, s101, v173
	v_mul_f32_e32 v169, s101, v169
	v_mul_f32_e32 v177, s101, v177
	v_mul_f32_e32 v191, s101, v191
	v_mul_f32_e32 v199, s101, v199
	v_mul_f32_e32 v146, v146, v244
	v_mul_f32_e32 v158, v158, v245
	v_mul_f32_e32 v154, v154, v246
	v_mul_f32_e32 v150, v150, v247
	v_mul_f32_e32 v147, v147, v244
	v_mul_f32_e32 v159, v159, v245
	v_mul_f32_e32 v155, v155, v246
	v_mul_f32_e32 v151, v151, v247
	v_mul_f32_e32 v148, v148, v244
	v_mul_f32_e32 v160, v160, v245
	v_mul_f32_e32 v156, v156, v246
	v_mul_f32_e32 v152, v152, v247
	v_mul_f32_e32 v149, v149, v244
	v_mul_f32_e32 v161, v161, v245
	v_mul_f32_e32 v157, v157, v246
	v_mul_f32_e32 v153, v153, v247
	v_mul_f32_e32 v116, v116, v244
	v_mul_f32_e32 v124, v124, v245
	v_mul_f32_e32 v112, v112, v246
	v_mul_f32_e32 v120, v120, v247
	v_mul_f32_e32 v117, v117, v244
	v_mul_f32_e32 v125, v125, v245
	v_mul_f32_e32 v113, v113, v246
	v_mul_f32_e32 v121, v121, v247
	v_mul_f32_e32 v118, v118, v244
	v_mul_f32_e32 v126, v126, v245
	v_mul_f32_e32 v114, v114, v246
	v_mul_f32_e32 v122, v122, v247
	v_mul_f32_e32 v119, v119, v244
	v_mul_f32_e32 v127, v127, v245
	v_mul_f32_e32 v115, v115, v246
	v_mul_f32_e32 v123, v123, v247
	v_mul_f32_e32 v48, v48, v248
	v_mul_f32_e32 v60, v60, v249
	v_mul_f32_e32 v56, v56, v250
	v_mul_f32_e32 v52, v52, v251
	v_mul_f32_e32 v49, v49, v248
	v_mul_f32_e32 v61, v61, v249
	v_mul_f32_e32 v57, v57, v250
	v_mul_f32_e32 v53, v53, v251
	v_mul_f32_e32 v50, v50, v248
	v_mul_f32_e32 v62, v62, v249
	v_mul_f32_e32 v58, v58, v250
	v_mul_f32_e32 v54, v54, v251
	v_mul_f32_e32 v51, v51, v248
	v_mul_f32_e32 v63, v63, v249
	v_mul_f32_e32 v59, v59, v250
	v_mul_f32_e32 v55, v55, v251
	v_mul_f32_e32 v20, v20, v248
	v_mul_f32_e32 v28, v28, v249
	v_mul_f32_e32 v16, v16, v250
	v_mul_f32_e32 v24, v24, v251
	v_mul_f32_e32 v21, v21, v248
	v_mul_f32_e32 v29, v29, v249
	v_mul_f32_e32 v17, v17, v250
	v_mul_f32_e32 v25, v25, v251
	v_mul_f32_e32 v22, v22, v248
	v_mul_f32_e32 v30, v30, v249
	v_mul_f32_e32 v18, v18, v250
	v_mul_f32_e32 v26, v26, v251
	v_mul_f32_e32 v23, v23, v248
	v_mul_f32_e32 v31, v31, v249
	v_mul_f32_e32 v19, v19, v250
	v_mul_f32_e32 v27, v27, v251
	s_waitcnt vmcnt(0)
	v_mul_f32_e32 v64, s101, v64
	v_mul_f32_e32 v65, s101, v65
	v_mul_f32_e32 v66, s101, v66
	v_mul_f32_e32 v67, s101, v67
	v_mul_f32_e32 v68, s101, v68
	v_mul_f32_e32 v69, s101, v69
	v_mul_f32_e32 v70, s101, v70
	v_mul_f32_e32 v71, s101, v71
	v_mul_f32_e32 v72, s101, v72
	v_mul_f32_e32 v73, s101, v73
	v_mul_f32_e32 v74, s101, v74
	v_mul_f32_e32 v75, s101, v75
	v_mul_f32_e32 v76, s101, v76
	v_mul_f32_e32 v77, s101, v77
	v_mul_f32_e32 v78, s101, v78
	v_mul_f32_e32 v79, s101, v79
	v_mul_f32_e32 v80, s101, v80
	v_mul_f32_e32 v81, s101, v81
	v_mul_f32_e32 v82, s101, v82
	v_mul_f32_e32 v83, s101, v83
	v_mul_f32_e32 v84, s101, v84
	v_mul_f32_e32 v85, s101, v85
	v_mul_f32_e32 v86, s101, v86
	v_mul_f32_e32 v87, s101, v87
	v_mul_f32_e32 v88, s101, v88
	v_mul_f32_e32 v89, s101, v89
	v_mul_f32_e32 v90, s101, v90
	v_mul_f32_e32 v91, s101, v91
	v_mul_f32_e32 v92, s101, v92
	v_mul_f32_e32 v93, s101, v93
	v_mul_f32_e32 v94, s101, v94
	v_mul_f32_e32 v95, s101, v95
	v_cndmask_b32_e64 v221, v146, 0, s[36:37]
	v_cndmask_b32_e64 v225, v146, 0, s[44:45]
	v_cndmask_b32_e64 v222, v158, v146, s[36:37]
	v_cndmask_b32_e64 v226, v158, v146, s[44:45]
	v_cndmask_b32_e64 v223, v154, v158, s[36:37]
	v_cndmask_b32_e64 v227, v154, v158, s[44:45]
	v_cndmask_b32_e64 v224, v150, v154, s[36:37]
	v_cndmask_b32_e64 v228, v150, v154, s[44:45]
	v_cndmask_b32_e64 v232, v147, 0, s[36:37]
	v_cndmask_b32_e64 v236, v147, 0, s[44:45]
	v_cndmask_b32_e64 v233, v159, v147, s[36:37]
	v_cndmask_b32_e64 v237, v159, v147, s[44:45]
	v_cndmask_b32_e64 v234, v155, v159, s[36:37]
	v_cndmask_b32_e64 v238, v155, v159, s[44:45]
	v_cndmask_b32_e64 v235, v151, v155, s[36:37]
	v_cndmask_b32_e64 v239, v151, v155, s[44:45]
	v_fma_f32 v200, v92, v146, v84
	v_fma_f32 v229, v92, v158, v84
	v_fma_f32 v230, v92, v154, v84
	v_fma_f32 v231, v92, v150, v84
	v_fma_f32 v201, v93, v147, v85
	v_fma_f32 v196, v93, v159, v85
	v_fma_f32 v197, v93, v155, v85
	v_fma_f32 v176, v93, v151, v85
	v_fmac_f32_dpp v200, v221, v88 row_ror:1 row_mask:0xf bank_mask:0xf
	v_fmac_f32_dpp v229, v222, v88 row_ror:1 row_mask:0xf bank_mask:0xf
	v_fmac_f32_dpp v230, v223, v88 row_ror:1 row_mask:0xf bank_mask:0xf
	v_fmac_f32_dpp v231, v224, v88 row_ror:1 row_mask:0xf bank_mask:0xf
	v_fmac_f32_dpp v201, v232, v89 row_ror:1 row_mask:0xf bank_mask:0xf
	v_fmac_f32_dpp v196, v233, v89 row_ror:1 row_mask:0xf bank_mask:0xf
	v_fmac_f32_dpp v197, v234, v89 row_ror:1 row_mask:0xf bank_mask:0xf
	v_fmac_f32_dpp v176, v235, v89 row_ror:1 row_mask:0xf bank_mask:0xf
	v_fmac_f32_dpp v200, v225, v80 row_ror:2 row_mask:0xf bank_mask:0xf
	v_fmac_f32_dpp v229, v226, v80 row_ror:2 row_mask:0xf bank_mask:0xf
	v_fmac_f32_dpp v230, v227, v80 row_ror:2 row_mask:0xf bank_mask:0xf
	v_fmac_f32_dpp v231, v228, v80 row_ror:2 row_mask:0xf bank_mask:0xf
	v_fmac_f32_dpp v201, v236, v81 row_ror:2 row_mask:0xf bank_mask:0xf
	v_fmac_f32_dpp v196, v237, v81 row_ror:2 row_mask:0xf bank_mask:0xf
	v_fmac_f32_dpp v197, v238, v81 row_ror:2 row_mask:0xf bank_mask:0xf
	v_fmac_f32_dpp v176, v239, v81 row_ror:2 row_mask:0xf bank_mask:0xf
	v_exp_f32_e32 v221, v200
	v_exp_f32_e32 v222, v229
	v_exp_f32_e32 v223, v230
	v_exp_f32_e32 v224, v231
	v_exp_f32_e32 v232, v201
	v_exp_f32_e32 v233, v196
	v_exp_f32_e32 v234, v197
	v_exp_f32_e32 v235, v176
	v_fma_f32 v221, v221, v170, v170
	v_fma_f32 v222, v222, v171, v171
	v_fma_f32 v223, v223, v172, v172
	v_fma_f32 v224, v224, v173, v173
	v_fma_f32 v232, v232, v170, v170
	v_fma_f32 v233, v233, v171, v171
	v_fma_f32 v234, v234, v172, v172
	v_fma_f32 v235, v235, v173, v173
	v_rcp_f32_e32 v221, v221
	v_rcp_f32_e32 v222, v222
	v_rcp_f32_e32 v223, v223
	v_rcp_f32_e32 v224, v224
	v_rcp_f32_e32 v232, v232
	v_rcp_f32_e32 v233, v233
	v_rcp_f32_e32 v234, v234
	v_rcp_f32_e32 v235, v235
	v_mul_f32_e32 v221, v200, v221
	v_mul_f32_e32 v222, v229, v222
	v_mul_f32_e32 v223, v230, v223
	v_mul_f32_e32 v224, v231, v224
	v_mul_f32_e32 v232, v201, v232
	v_mul_f32_e32 v233, v196, v233
	v_mul_f32_e32 v234, v197, v234
	v_mul_f32_e32 v235, v176, v235
	v_mul_f32_e32 v192, v140, v244
	v_mul_f32_e32 v193, v141, v244
	v_mul_f32_e32 v140, v221, v140
	v_mul_f32_e32 v136, v222, v136
	v_mul_f32_e32 v132, v223, v132
	v_mul_f32_e32 v128, v224, v128
	v_mul_f32_e32 v141, v232, v141
	v_mul_f32_e32 v137, v233, v137
	v_mul_f32_e32 v133, v234, v133
	v_mul_f32_e32 v129, v235, v129
	v_cndmask_b32_e64 v221, v148, 0, s[36:37]
	v_cndmask_b32_e64 v225, v148, 0, s[44:45]
	v_cndmask_b32_e64 v222, v160, v148, s[36:37]
	v_cndmask_b32_e64 v226, v160, v148, s[44:45]
	v_cndmask_b32_e64 v223, v156, v160, s[36:37]
	v_cndmask_b32_e64 v227, v156, v160, s[44:45]
	v_cndmask_b32_e64 v224, v152, v156, s[36:37]
	v_cndmask_b32_e64 v228, v152, v156, s[44:45]
	v_cndmask_b32_e64 v232, v149, 0, s[36:37]
	v_cndmask_b32_e64 v236, v149, 0, s[44:45]
	v_cndmask_b32_e64 v233, v161, v149, s[36:37]
	v_cndmask_b32_e64 v237, v161, v149, s[44:45]
	v_cndmask_b32_e64 v234, v157, v161, s[36:37]
	v_cndmask_b32_e64 v238, v157, v161, s[44:45]
	v_cndmask_b32_e64 v235, v153, v157, s[36:37]
	v_cndmask_b32_e64 v239, v153, v157, s[44:45]
	v_fma_f32 v202, v94, v148, v86
	v_fma_f32 v229, v94, v160, v86
	v_fma_f32 v230, v94, v156, v86
	v_fma_f32 v231, v94, v152, v86
	v_fma_f32 v203, v95, v149, v87
	v_fma_f32 v196, v95, v161, v87
	v_fma_f32 v197, v95, v157, v87
	v_fma_f32 v176, v95, v153, v87
	v_fmac_f32_dpp v202, v221, v90 row_ror:1 row_mask:0xf bank_mask:0xf
	v_fmac_f32_dpp v229, v222, v90 row_ror:1 row_mask:0xf bank_mask:0xf
	v_fmac_f32_dpp v230, v223, v90 row_ror:1 row_mask:0xf bank_mask:0xf
	v_fmac_f32_dpp v231, v224, v90 row_ror:1 row_mask:0xf bank_mask:0xf
	v_fmac_f32_dpp v203, v232, v91 row_ror:1 row_mask:0xf bank_mask:0xf
	v_fmac_f32_dpp v196, v233, v91 row_ror:1 row_mask:0xf bank_mask:0xf
	v_fmac_f32_dpp v197, v234, v91 row_ror:1 row_mask:0xf bank_mask:0xf
	v_fmac_f32_dpp v176, v235, v91 row_ror:1 row_mask:0xf bank_mask:0xf
	v_fmac_f32_dpp v202, v225, v82 row_ror:2 row_mask:0xf bank_mask:0xf
	v_fmac_f32_dpp v229, v226, v82 row_ror:2 row_mask:0xf bank_mask:0xf
	v_fmac_f32_dpp v230, v227, v82 row_ror:2 row_mask:0xf bank_mask:0xf
	v_fmac_f32_dpp v231, v228, v82 row_ror:2 row_mask:0xf bank_mask:0xf
	v_fmac_f32_dpp v203, v236, v83 row_ror:2 row_mask:0xf bank_mask:0xf
	v_fmac_f32_dpp v196, v237, v83 row_ror:2 row_mask:0xf bank_mask:0xf
	v_fmac_f32_dpp v197, v238, v83 row_ror:2 row_mask:0xf bank_mask:0xf
	v_fmac_f32_dpp v176, v239, v83 row_ror:2 row_mask:0xf bank_mask:0xf
	v_exp_f32_e32 v221, v202
	v_exp_f32_e32 v222, v229
	v_exp_f32_e32 v223, v230
	v_exp_f32_e32 v224, v231
	v_exp_f32_e32 v232, v203
	v_exp_f32_e32 v233, v196
	v_exp_f32_e32 v234, v197
	v_exp_f32_e32 v235, v176
	v_fma_f32 v221, v221, v170, v170
	v_fma_f32 v222, v222, v171, v171
	v_fma_f32 v223, v223, v172, v172
	v_fma_f32 v224, v224, v173, v173
	v_fma_f32 v232, v232, v170, v170
	v_fma_f32 v233, v233, v171, v171
	v_fma_f32 v234, v234, v172, v172
	v_fma_f32 v235, v235, v173, v173
	v_rcp_f32_e32 v221, v221
	v_rcp_f32_e32 v222, v222
	v_rcp_f32_e32 v223, v223
	v_rcp_f32_e32 v224, v224
	v_rcp_f32_e32 v232, v232
	v_rcp_f32_e32 v233, v233
	v_rcp_f32_e32 v234, v234
	v_rcp_f32_e32 v235, v235
	v_mul_f32_e32 v221, v202, v221
	v_mul_f32_e32 v222, v229, v222
	v_mul_f32_e32 v223, v230, v223
	v_mul_f32_e32 v224, v231, v224
	v_mul_f32_e32 v232, v203, v232
	v_mul_f32_e32 v233, v196, v233
	v_mul_f32_e32 v234, v197, v234
	v_mul_f32_e32 v235, v176, v235
	v_mul_f32_e32 v194, v142, v244
	v_mul_f32_e32 v195, v143, v244
	v_mul_f32_e32 v142, v221, v142
	v_mul_f32_e32 v138, v222, v138
	v_mul_f32_e32 v134, v223, v134
	v_mul_f32_e32 v130, v224, v130
	v_mul_f32_e32 v143, v232, v143
	v_mul_f32_e32 v139, v233, v139
	v_mul_f32_e32 v135, v234, v135
	v_mul_f32_e32 v131, v235, v131
	v_cndmask_b32_e64 v221, v116, 0, s[36:37]
	v_cndmask_b32_e64 v225, v116, 0, s[44:45]
	v_cndmask_b32_e64 v222, v124, v116, s[36:37]
	v_cndmask_b32_e64 v226, v124, v116, s[44:45]
	v_cndmask_b32_e64 v223, v112, v124, s[36:37]
	v_cndmask_b32_e64 v227, v112, v124, s[44:45]
	v_cndmask_b32_e64 v224, v120, v112, s[36:37]
	v_cndmask_b32_e64 v228, v120, v112, s[44:45]
	v_cndmask_b32_e64 v232, v117, 0, s[36:37]
	v_cndmask_b32_e64 v236, v117, 0, s[44:45]
	v_cndmask_b32_e64 v233, v125, v117, s[36:37]
	v_cndmask_b32_e64 v237, v125, v117, s[44:45]
	v_cndmask_b32_e64 v234, v113, v125, s[36:37]
	v_cndmask_b32_e64 v238, v113, v125, s[44:45]
	v_cndmask_b32_e64 v235, v121, v113, s[36:37]
	v_cndmask_b32_e64 v239, v121, v113, s[44:45]
	v_fma_f32 v204, v76, v116, v68
	v_fma_f32 v229, v76, v124, v68
	v_fma_f32 v230, v76, v112, v68
	v_fma_f32 v231, v76, v120, v68
	v_fma_f32 v205, v77, v117, v69
	v_fma_f32 v196, v77, v125, v69
	v_fma_f32 v197, v77, v113, v69
	v_fma_f32 v176, v77, v121, v69
	v_fmac_f32_dpp v204, v221, v72 row_ror:1 row_mask:0xf bank_mask:0xf
	v_fmac_f32_dpp v229, v222, v72 row_ror:1 row_mask:0xf bank_mask:0xf
	v_fmac_f32_dpp v230, v223, v72 row_ror:1 row_mask:0xf bank_mask:0xf
	v_fmac_f32_dpp v231, v224, v72 row_ror:1 row_mask:0xf bank_mask:0xf
	v_fmac_f32_dpp v205, v232, v73 row_ror:1 row_mask:0xf bank_mask:0xf
	v_fmac_f32_dpp v196, v233, v73 row_ror:1 row_mask:0xf bank_mask:0xf
	v_fmac_f32_dpp v197, v234, v73 row_ror:1 row_mask:0xf bank_mask:0xf
	v_fmac_f32_dpp v176, v235, v73 row_ror:1 row_mask:0xf bank_mask:0xf
	v_fmac_f32_dpp v204, v225, v64 row_ror:2 row_mask:0xf bank_mask:0xf
	v_fmac_f32_dpp v229, v226, v64 row_ror:2 row_mask:0xf bank_mask:0xf
	v_fmac_f32_dpp v230, v227, v64 row_ror:2 row_mask:0xf bank_mask:0xf
	v_fmac_f32_dpp v231, v228, v64 row_ror:2 row_mask:0xf bank_mask:0xf
	v_fmac_f32_dpp v205, v236, v65 row_ror:2 row_mask:0xf bank_mask:0xf
	v_fmac_f32_dpp v196, v237, v65 row_ror:2 row_mask:0xf bank_mask:0xf
	v_fmac_f32_dpp v197, v238, v65 row_ror:2 row_mask:0xf bank_mask:0xf
	v_fmac_f32_dpp v176, v239, v65 row_ror:2 row_mask:0xf bank_mask:0xf
	v_exp_f32_e32 v221, v204
	v_exp_f32_e32 v222, v229
	v_exp_f32_e32 v223, v230
	v_exp_f32_e32 v224, v231
	v_exp_f32_e32 v232, v205
	v_exp_f32_e32 v233, v196
	v_exp_f32_e32 v234, v197
	v_exp_f32_e32 v235, v176
	v_fma_f32 v221, v221, v170, v170
	v_fma_f32 v222, v222, v171, v171
	v_fma_f32 v223, v223, v172, v172
	v_fma_f32 v224, v224, v173, v173
	v_fma_f32 v232, v232, v170, v170
	v_fma_f32 v233, v233, v171, v171
	v_fma_f32 v234, v234, v172, v172
	v_fma_f32 v235, v235, v173, v173
	v_rcp_f32_e32 v221, v221
	v_rcp_f32_e32 v222, v222
	v_rcp_f32_e32 v223, v223
	v_rcp_f32_e32 v224, v224
	v_rcp_f32_e32 v232, v232
	v_rcp_f32_e32 v233, v233
	v_rcp_f32_e32 v234, v234
	v_rcp_f32_e32 v235, v235
	v_mul_f32_e32 v221, v204, v221
	v_mul_f32_e32 v222, v229, v222
	v_mul_f32_e32 v223, v230, v223
	v_mul_f32_e32 v224, v231, v224
	v_mul_f32_e32 v232, v205, v232
	v_mul_f32_e32 v233, v196, v233
	v_mul_f32_e32 v234, v197, v234
	v_mul_f32_e32 v235, v176, v235
	v_mul_f32_e32 v240, v108, v244
	v_mul_f32_e32 v241, v109, v244
	v_mul_f32_e32 v108, v221, v108
	v_mul_f32_e32 v104, v222, v104
	v_mul_f32_e32 v100, v223, v100
	v_mul_f32_e32 v96, v224, v96
	v_mul_f32_e32 v109, v232, v109
	v_mul_f32_e32 v105, v233, v105
	v_mul_f32_e32 v101, v234, v101
	v_mul_f32_e32 v97, v235, v97
	v_cndmask_b32_e64 v221, v118, 0, s[36:37]
	v_cndmask_b32_e64 v225, v118, 0, s[44:45]
	v_cndmask_b32_e64 v222, v126, v118, s[36:37]
	v_cndmask_b32_e64 v226, v126, v118, s[44:45]
	v_cndmask_b32_e64 v223, v114, v126, s[36:37]
	v_cndmask_b32_e64 v227, v114, v126, s[44:45]
	v_cndmask_b32_e64 v224, v122, v114, s[36:37]
	v_cndmask_b32_e64 v228, v122, v114, s[44:45]
	v_cndmask_b32_e64 v232, v119, 0, s[36:37]
	v_cndmask_b32_e64 v236, v119, 0, s[44:45]
	v_cndmask_b32_e64 v233, v127, v119, s[36:37]
	v_cndmask_b32_e64 v237, v127, v119, s[44:45]
	v_cndmask_b32_e64 v234, v115, v127, s[36:37]
	v_cndmask_b32_e64 v238, v115, v127, s[44:45]
	v_cndmask_b32_e64 v235, v123, v115, s[36:37]
	v_cndmask_b32_e64 v239, v123, v115, s[44:45]
	v_fma_f32 v206, v78, v118, v70
	v_fma_f32 v229, v78, v126, v70
	v_fma_f32 v230, v78, v114, v70
	v_fma_f32 v231, v78, v122, v70
	v_fma_f32 v207, v79, v119, v71
	v_fma_f32 v196, v79, v127, v71
	v_fma_f32 v197, v79, v115, v71
	v_fma_f32 v176, v79, v123, v71
	v_fmac_f32_dpp v206, v221, v74 row_ror:1 row_mask:0xf bank_mask:0xf
	v_fmac_f32_dpp v229, v222, v74 row_ror:1 row_mask:0xf bank_mask:0xf
	v_fmac_f32_dpp v230, v223, v74 row_ror:1 row_mask:0xf bank_mask:0xf
	v_fmac_f32_dpp v231, v224, v74 row_ror:1 row_mask:0xf bank_mask:0xf
	v_fmac_f32_dpp v207, v232, v75 row_ror:1 row_mask:0xf bank_mask:0xf
	v_fmac_f32_dpp v196, v233, v75 row_ror:1 row_mask:0xf bank_mask:0xf
	v_fmac_f32_dpp v197, v234, v75 row_ror:1 row_mask:0xf bank_mask:0xf
	v_fmac_f32_dpp v176, v235, v75 row_ror:1 row_mask:0xf bank_mask:0xf
	v_fmac_f32_dpp v206, v225, v66 row_ror:2 row_mask:0xf bank_mask:0xf
	v_fmac_f32_dpp v229, v226, v66 row_ror:2 row_mask:0xf bank_mask:0xf
	v_fmac_f32_dpp v230, v227, v66 row_ror:2 row_mask:0xf bank_mask:0xf
	v_fmac_f32_dpp v231, v228, v66 row_ror:2 row_mask:0xf bank_mask:0xf
	v_fmac_f32_dpp v207, v236, v67 row_ror:2 row_mask:0xf bank_mask:0xf
	v_fmac_f32_dpp v196, v237, v67 row_ror:2 row_mask:0xf bank_mask:0xf
	v_fmac_f32_dpp v197, v238, v67 row_ror:2 row_mask:0xf bank_mask:0xf
	v_fmac_f32_dpp v176, v239, v67 row_ror:2 row_mask:0xf bank_mask:0xf
	v_exp_f32_e32 v221, v206
	v_exp_f32_e32 v222, v229
	v_exp_f32_e32 v223, v230
	v_exp_f32_e32 v224, v231
	v_exp_f32_e32 v232, v207
	v_exp_f32_e32 v233, v196
	v_exp_f32_e32 v234, v197
	v_exp_f32_e32 v235, v176
	v_fma_f32 v221, v221, v170, v170
	v_fma_f32 v222, v222, v171, v171
	v_fma_f32 v223, v223, v172, v172
	v_fma_f32 v224, v224, v173, v173
	v_fma_f32 v232, v232, v170, v170
	v_fma_f32 v233, v233, v171, v171
	v_fma_f32 v234, v234, v172, v172
	v_fma_f32 v235, v235, v173, v173
	v_rcp_f32_e32 v221, v221
	v_rcp_f32_e32 v222, v222
	v_rcp_f32_e32 v223, v223
	v_rcp_f32_e32 v224, v224
	v_rcp_f32_e32 v232, v232
	v_rcp_f32_e32 v233, v233
	v_rcp_f32_e32 v234, v234
	v_rcp_f32_e32 v235, v235
	v_mul_f32_e32 v221, v206, v221
	v_mul_f32_e32 v222, v229, v222
	v_mul_f32_e32 v223, v230, v223
	v_mul_f32_e32 v224, v231, v224
	v_mul_f32_e32 v232, v207, v232
	v_mul_f32_e32 v233, v196, v233
	v_mul_f32_e32 v234, v197, v234
	v_mul_f32_e32 v235, v176, v235
	v_mul_f32_e32 v242, v110, v244
	v_mul_f32_e32 v243, v111, v244
	v_mul_f32_e32 v110, v221, v110
	v_mul_f32_e32 v106, v222, v106
	v_mul_f32_e32 v102, v223, v102
	v_mul_f32_e32 v98, v224, v98
	v_mul_f32_e32 v111, v232, v111
	v_mul_f32_e32 v107, v233, v107
	v_mul_f32_e32 v103, v234, v103
	v_mul_f32_e32 v99, v235, v99
	v_cvt_pk_bf16_f32 v140, v140, v141
	v_cvt_pk_bf16_f32 v141, v142, v143
	v_cvt_pk_bf16_f32 v142, v108, v109
	v_cvt_pk_bf16_f32 v143, v110, v111
	v_cvt_pk_bf16_f32 v136, v136, v137
	v_cvt_pk_bf16_f32 v137, v138, v139
	v_cvt_pk_bf16_f32 v138, v104, v105
	v_cvt_pk_bf16_f32 v139, v106, v107
	v_cvt_pk_bf16_f32 v132, v132, v133
	v_cvt_pk_bf16_f32 v133, v134, v135
	v_cvt_pk_bf16_f32 v134, v100, v101
	v_cvt_pk_bf16_f32 v135, v102, v103
	v_cvt_pk_bf16_f32 v128, v128, v129
	v_cvt_pk_bf16_f32 v129, v130, v131
	v_cvt_pk_bf16_f32 v130, v96, v97
	v_cvt_pk_bf16_f32 v131, v98, v99
	v_mul_f32_e32 v200, 0xbf317218, v200
	v_mul_f32_e32 v201, 0xbf317218, v201
	v_mul_f32_e32 v202, 0xbf317218, v202
	v_mul_f32_e32 v203, 0xbf317218, v203
	v_mul_f32_e32 v204, 0xbf317218, v204
	v_mul_f32_e32 v205, 0xbf317218, v205
	v_mul_f32_e32 v206, 0xbf317218, v206
	v_mul_f32_e32 v207, 0xbf317218, v207
	v_or_b32_e32 v170, s11, v216
	v_mul_u32_u24_e32 v170, s10, v170
	v_lshl_add_u32 v170, v170, 2, v190
	s_and_saveexec_b64 s[0:1], s[42:43]
	global_store_dwordx4 v170, v[200:203], s[50:51]
	global_store_dwordx4 v170, v[204:207], s[50:51] offset:16
	global_store_dwordx4 v170, v[192:195], s[92:93]
	global_store_dwordx4 v170, v[240:243], s[92:93] offset:16
	s_or_b64 exec, exec, s[0:1]
	v_add_u32_e32 v171, s11, v218
	v_mul_u32_u24_e32 v171, s10, v171
	v_lshl_add_u32 v171, v171, 2, v190
	s_and_saveexec_b64 s[0:1], s[44:45]
	global_store_dwordx4 v171, v[150:153], s[52:53]
	global_store_dwordx4 v171, v[120:123], s[52:53] offset:16
	s_or_b64 exec, exec, s[0:1]
	v_mad_u32_u24 v172, v198, s20, v189
	s_and_saveexec_b64 s[0:1], s[40:41]
	global_store_dwordx4 v172, v[140:143], s[94:95]
	s_or_b64 exec, exec, s[0:1]
	v_add_u32_e32 v172, 0x16000, v172
	global_store_dwordx4 v172, v[136:139], s[94:95]
	v_add_u32_e32 v172, 0x16000, v172
	global_store_dwordx4 v172, v[132:135], s[94:95]
	v_add_u32_e32 v172, 0x16000, v172
	global_store_dwordx4 v172, v[128:131], s[94:95]
	s_add_i32 s11, s11, 4
	v_cndmask_b32_e64 v221, v48, 0, s[36:37]
	v_cndmask_b32_e64 v225, v48, 0, s[44:45]
	v_cndmask_b32_e64 v222, v60, v48, s[36:37]
	v_cndmask_b32_e64 v226, v60, v48, s[44:45]
	v_cndmask_b32_e64 v223, v56, v60, s[36:37]
	v_cndmask_b32_e64 v227, v56, v60, s[44:45]
	v_cndmask_b32_e64 v224, v52, v56, s[36:37]
	v_cndmask_b32_e64 v228, v52, v56, s[44:45]
	v_cndmask_b32_e64 v232, v49, 0, s[36:37]
	v_cndmask_b32_e64 v236, v49, 0, s[44:45]
	v_cndmask_b32_e64 v233, v61, v49, s[36:37]
	v_cndmask_b32_e64 v237, v61, v49, s[44:45]
	v_cndmask_b32_e64 v234, v57, v61, s[36:37]
	v_cndmask_b32_e64 v238, v57, v61, s[44:45]
	v_cndmask_b32_e64 v235, v53, v57, s[36:37]
	v_cndmask_b32_e64 v239, v53, v57, s[44:45]
	v_fma_f32 v200, v92, v48, v84
	v_fma_f32 v229, v92, v60, v84
	v_fma_f32 v230, v92, v56, v84
	v_fma_f32 v231, v92, v52, v84
	v_fma_f32 v201, v93, v49, v85
	v_fma_f32 v196, v93, v61, v85
	v_fma_f32 v197, v93, v57, v85
	v_fma_f32 v176, v93, v53, v85
	v_fmac_f32_dpp v200, v221, v88 row_ror:1 row_mask:0xf bank_mask:0xf
	v_fmac_f32_dpp v229, v222, v88 row_ror:1 row_mask:0xf bank_mask:0xf
	v_fmac_f32_dpp v230, v223, v88 row_ror:1 row_mask:0xf bank_mask:0xf
	v_fmac_f32_dpp v231, v224, v88 row_ror:1 row_mask:0xf bank_mask:0xf
	v_fmac_f32_dpp v201, v232, v89 row_ror:1 row_mask:0xf bank_mask:0xf
	v_fmac_f32_dpp v196, v233, v89 row_ror:1 row_mask:0xf bank_mask:0xf
	v_fmac_f32_dpp v197, v234, v89 row_ror:1 row_mask:0xf bank_mask:0xf
	v_fmac_f32_dpp v176, v235, v89 row_ror:1 row_mask:0xf bank_mask:0xf
	v_fmac_f32_dpp v200, v225, v80 row_ror:2 row_mask:0xf bank_mask:0xf
	v_fmac_f32_dpp v229, v226, v80 row_ror:2 row_mask:0xf bank_mask:0xf
	v_fmac_f32_dpp v230, v227, v80 row_ror:2 row_mask:0xf bank_mask:0xf
	v_fmac_f32_dpp v231, v228, v80 row_ror:2 row_mask:0xf bank_mask:0xf
	v_fmac_f32_dpp v201, v236, v81 row_ror:2 row_mask:0xf bank_mask:0xf
	v_fmac_f32_dpp v196, v237, v81 row_ror:2 row_mask:0xf bank_mask:0xf
	v_fmac_f32_dpp v197, v238, v81 row_ror:2 row_mask:0xf bank_mask:0xf
	v_fmac_f32_dpp v176, v239, v81 row_ror:2 row_mask:0xf bank_mask:0xf
	v_exp_f32_e32 v221, v200
	v_exp_f32_e32 v222, v229
	v_exp_f32_e32 v223, v230
	v_exp_f32_e32 v224, v231
	v_exp_f32_e32 v232, v201
	v_exp_f32_e32 v233, v196
	v_exp_f32_e32 v234, v197
	v_exp_f32_e32 v235, v176
	v_fma_f32 v221, v221, v169, v169
	v_fma_f32 v222, v222, v177, v177
	v_fma_f32 v223, v223, v191, v191
	v_fma_f32 v224, v224, v199, v199
	v_fma_f32 v232, v232, v169, v169
	v_fma_f32 v233, v233, v177, v177
	v_fma_f32 v234, v234, v191, v191
	v_fma_f32 v235, v235, v199, v199
	v_rcp_f32_e32 v221, v221
	v_rcp_f32_e32 v222, v222
	v_rcp_f32_e32 v223, v223
	v_rcp_f32_e32 v224, v224
	v_rcp_f32_e32 v232, v232
	v_rcp_f32_e32 v233, v233
	v_rcp_f32_e32 v234, v234
	v_rcp_f32_e32 v235, v235
	v_mul_f32_e32 v221, v200, v221
	v_mul_f32_e32 v222, v229, v222
	v_mul_f32_e32 v223, v230, v223
	v_mul_f32_e32 v224, v231, v224
	v_mul_f32_e32 v232, v201, v232
	v_mul_f32_e32 v233, v196, v233
	v_mul_f32_e32 v234, v197, v234
	v_mul_f32_e32 v235, v176, v235
	v_mul_f32_e32 v192, v44, v248
	v_mul_f32_e32 v193, v45, v248
	v_mul_f32_e32 v44, v221, v44
	v_mul_f32_e32 v40, v222, v40
	v_mul_f32_e32 v36, v223, v36
	v_mul_f32_e32 v32, v224, v32
	v_mul_f32_e32 v45, v232, v45
	v_mul_f32_e32 v41, v233, v41
	v_mul_f32_e32 v37, v234, v37
	v_mul_f32_e32 v33, v235, v33
	v_cndmask_b32_e64 v221, v50, 0, s[36:37]
	v_cndmask_b32_e64 v225, v50, 0, s[44:45]
	v_cndmask_b32_e64 v222, v62, v50, s[36:37]
	v_cndmask_b32_e64 v226, v62, v50, s[44:45]
	v_cndmask_b32_e64 v223, v58, v62, s[36:37]
	v_cndmask_b32_e64 v227, v58, v62, s[44:45]
	v_cndmask_b32_e64 v224, v54, v58, s[36:37]
	v_cndmask_b32_e64 v228, v54, v58, s[44:45]
	v_cndmask_b32_e64 v232, v51, 0, s[36:37]
	v_cndmask_b32_e64 v236, v51, 0, s[44:45]
	v_cndmask_b32_e64 v233, v63, v51, s[36:37]
	v_cndmask_b32_e64 v237, v63, v51, s[44:45]
	v_cndmask_b32_e64 v234, v59, v63, s[36:37]
	v_cndmask_b32_e64 v238, v59, v63, s[44:45]
	v_cndmask_b32_e64 v235, v55, v59, s[36:37]
	v_cndmask_b32_e64 v239, v55, v59, s[44:45]
	v_fma_f32 v202, v94, v50, v86
	v_fma_f32 v229, v94, v62, v86
	v_fma_f32 v230, v94, v58, v86
	v_fma_f32 v231, v94, v54, v86
	v_fma_f32 v203, v95, v51, v87
	v_fma_f32 v196, v95, v63, v87
	v_fma_f32 v197, v95, v59, v87
	v_fma_f32 v176, v95, v55, v87
	v_fmac_f32_dpp v202, v221, v90 row_ror:1 row_mask:0xf bank_mask:0xf
	v_fmac_f32_dpp v229, v222, v90 row_ror:1 row_mask:0xf bank_mask:0xf
	v_fmac_f32_dpp v230, v223, v90 row_ror:1 row_mask:0xf bank_mask:0xf
	v_fmac_f32_dpp v231, v224, v90 row_ror:1 row_mask:0xf bank_mask:0xf
	v_fmac_f32_dpp v203, v232, v91 row_ror:1 row_mask:0xf bank_mask:0xf
	v_fmac_f32_dpp v196, v233, v91 row_ror:1 row_mask:0xf bank_mask:0xf
	v_fmac_f32_dpp v197, v234, v91 row_ror:1 row_mask:0xf bank_mask:0xf
	v_fmac_f32_dpp v176, v235, v91 row_ror:1 row_mask:0xf bank_mask:0xf
	v_fmac_f32_dpp v202, v225, v82 row_ror:2 row_mask:0xf bank_mask:0xf
	v_fmac_f32_dpp v229, v226, v82 row_ror:2 row_mask:0xf bank_mask:0xf
	v_fmac_f32_dpp v230, v227, v82 row_ror:2 row_mask:0xf bank_mask:0xf
	v_fmac_f32_dpp v231, v228, v82 row_ror:2 row_mask:0xf bank_mask:0xf
	v_fmac_f32_dpp v203, v236, v83 row_ror:2 row_mask:0xf bank_mask:0xf
	v_fmac_f32_dpp v196, v237, v83 row_ror:2 row_mask:0xf bank_mask:0xf
	v_fmac_f32_dpp v197, v238, v83 row_ror:2 row_mask:0xf bank_mask:0xf
	v_fmac_f32_dpp v176, v239, v83 row_ror:2 row_mask:0xf bank_mask:0xf
	v_exp_f32_e32 v221, v202
	v_exp_f32_e32 v222, v229
	v_exp_f32_e32 v223, v230
	v_exp_f32_e32 v224, v231
	v_exp_f32_e32 v232, v203
	v_exp_f32_e32 v233, v196
	v_exp_f32_e32 v234, v197
	v_exp_f32_e32 v235, v176
	v_fma_f32 v221, v221, v169, v169
	v_fma_f32 v222, v222, v177, v177
	v_fma_f32 v223, v223, v191, v191
	v_fma_f32 v224, v224, v199, v199
	v_fma_f32 v232, v232, v169, v169
	v_fma_f32 v233, v233, v177, v177
	v_fma_f32 v234, v234, v191, v191
	v_fma_f32 v235, v235, v199, v199
	v_rcp_f32_e32 v221, v221
	v_rcp_f32_e32 v222, v222
	v_rcp_f32_e32 v223, v223
	v_rcp_f32_e32 v224, v224
	v_rcp_f32_e32 v232, v232
	v_rcp_f32_e32 v233, v233
	v_rcp_f32_e32 v234, v234
	v_rcp_f32_e32 v235, v235
	v_mul_f32_e32 v221, v202, v221
	v_mul_f32_e32 v222, v229, v222
	v_mul_f32_e32 v223, v230, v223
	v_mul_f32_e32 v224, v231, v224
	v_mul_f32_e32 v232, v203, v232
	v_mul_f32_e32 v233, v196, v233
	v_mul_f32_e32 v234, v197, v234
	v_mul_f32_e32 v235, v176, v235
	v_mul_f32_e32 v194, v46, v248
	v_mul_f32_e32 v195, v47, v248
	v_mul_f32_e32 v46, v221, v46
	v_mul_f32_e32 v42, v222, v42
	v_mul_f32_e32 v38, v223, v38
	v_mul_f32_e32 v34, v224, v34
	v_mul_f32_e32 v47, v232, v47
	v_mul_f32_e32 v43, v233, v43
	v_mul_f32_e32 v39, v234, v39
	v_mul_f32_e32 v35, v235, v35
	v_cndmask_b32_e64 v221, v20, 0, s[36:37]
	v_cndmask_b32_e64 v225, v20, 0, s[44:45]
	v_cndmask_b32_e64 v222, v28, v20, s[36:37]
	v_cndmask_b32_e64 v226, v28, v20, s[44:45]
	v_cndmask_b32_e64 v223, v16, v28, s[36:37]
	v_cndmask_b32_e64 v227, v16, v28, s[44:45]
	v_cndmask_b32_e64 v224, v24, v16, s[36:37]
	v_cndmask_b32_e64 v228, v24, v16, s[44:45]
	v_cndmask_b32_e64 v232, v21, 0, s[36:37]
	v_cndmask_b32_e64 v236, v21, 0, s[44:45]
	v_cndmask_b32_e64 v233, v29, v21, s[36:37]
	v_cndmask_b32_e64 v237, v29, v21, s[44:45]
	v_cndmask_b32_e64 v234, v17, v29, s[36:37]
	v_cndmask_b32_e64 v238, v17, v29, s[44:45]
	v_cndmask_b32_e64 v235, v25, v17, s[36:37]
	v_cndmask_b32_e64 v239, v25, v17, s[44:45]
	v_fma_f32 v204, v76, v20, v68
	v_fma_f32 v229, v76, v28, v68
	v_fma_f32 v230, v76, v16, v68
	v_fma_f32 v231, v76, v24, v68
	v_fma_f32 v205, v77, v21, v69
	v_fma_f32 v196, v77, v29, v69
	v_fma_f32 v197, v77, v17, v69
	v_fma_f32 v176, v77, v25, v69
	v_fmac_f32_dpp v204, v221, v72 row_ror:1 row_mask:0xf bank_mask:0xf
	v_fmac_f32_dpp v229, v222, v72 row_ror:1 row_mask:0xf bank_mask:0xf
	v_fmac_f32_dpp v230, v223, v72 row_ror:1 row_mask:0xf bank_mask:0xf
	v_fmac_f32_dpp v231, v224, v72 row_ror:1 row_mask:0xf bank_mask:0xf
	v_fmac_f32_dpp v205, v232, v73 row_ror:1 row_mask:0xf bank_mask:0xf
	v_fmac_f32_dpp v196, v233, v73 row_ror:1 row_mask:0xf bank_mask:0xf
	v_fmac_f32_dpp v197, v234, v73 row_ror:1 row_mask:0xf bank_mask:0xf
	v_fmac_f32_dpp v176, v235, v73 row_ror:1 row_mask:0xf bank_mask:0xf
	v_fmac_f32_dpp v204, v225, v64 row_ror:2 row_mask:0xf bank_mask:0xf
	v_fmac_f32_dpp v229, v226, v64 row_ror:2 row_mask:0xf bank_mask:0xf
	v_fmac_f32_dpp v230, v227, v64 row_ror:2 row_mask:0xf bank_mask:0xf
	v_fmac_f32_dpp v231, v228, v64 row_ror:2 row_mask:0xf bank_mask:0xf
	v_fmac_f32_dpp v205, v236, v65 row_ror:2 row_mask:0xf bank_mask:0xf
	v_fmac_f32_dpp v196, v237, v65 row_ror:2 row_mask:0xf bank_mask:0xf
	v_fmac_f32_dpp v197, v238, v65 row_ror:2 row_mask:0xf bank_mask:0xf
	v_fmac_f32_dpp v176, v239, v65 row_ror:2 row_mask:0xf bank_mask:0xf
	v_exp_f32_e32 v221, v204
	v_exp_f32_e32 v222, v229
	v_exp_f32_e32 v223, v230
	v_exp_f32_e32 v224, v231
	v_exp_f32_e32 v232, v205
	v_exp_f32_e32 v233, v196
	v_exp_f32_e32 v234, v197
	v_exp_f32_e32 v235, v176
	v_fma_f32 v221, v221, v169, v169
	v_fma_f32 v222, v222, v177, v177
	v_fma_f32 v223, v223, v191, v191
	v_fma_f32 v224, v224, v199, v199
	v_fma_f32 v232, v232, v169, v169
	v_fma_f32 v233, v233, v177, v177
	v_fma_f32 v234, v234, v191, v191
	v_fma_f32 v235, v235, v199, v199
	v_rcp_f32_e32 v221, v221
	v_rcp_f32_e32 v222, v222
	v_rcp_f32_e32 v223, v223
	v_rcp_f32_e32 v224, v224
	v_rcp_f32_e32 v232, v232
	v_rcp_f32_e32 v233, v233
	v_rcp_f32_e32 v234, v234
	v_rcp_f32_e32 v235, v235
	v_mul_f32_e32 v221, v204, v221
	v_mul_f32_e32 v222, v229, v222
	v_mul_f32_e32 v223, v230, v223
	v_mul_f32_e32 v224, v231, v224
	v_mul_f32_e32 v232, v205, v232
	v_mul_f32_e32 v233, v196, v233
	v_mul_f32_e32 v234, v197, v234
	v_mul_f32_e32 v235, v176, v235
	v_mul_f32_e32 v240, v12, v248
	v_mul_f32_e32 v241, v13, v248
	v_mul_f32_e32 v12, v221, v12
	v_mul_f32_e32 v8, v222, v8
	v_mul_f32_e32 v4, v223, v4
	v_mul_f32_e32 v0, v224, v0
	v_mul_f32_e32 v13, v232, v13
	v_mul_f32_e32 v9, v233, v9
	v_mul_f32_e32 v5, v234, v5
	v_mul_f32_e32 v1, v235, v1
	v_cndmask_b32_e64 v221, v22, 0, s[36:37]
	v_cndmask_b32_e64 v225, v22, 0, s[44:45]
	v_cndmask_b32_e64 v222, v30, v22, s[36:37]
	v_cndmask_b32_e64 v226, v30, v22, s[44:45]
	v_cndmask_b32_e64 v223, v18, v30, s[36:37]
	v_cndmask_b32_e64 v227, v18, v30, s[44:45]
	v_cndmask_b32_e64 v224, v26, v18, s[36:37]
	v_cndmask_b32_e64 v228, v26, v18, s[44:45]
	v_cndmask_b32_e64 v232, v23, 0, s[36:37]
	v_cndmask_b32_e64 v236, v23, 0, s[44:45]
	v_cndmask_b32_e64 v233, v31, v23, s[36:37]
	v_cndmask_b32_e64 v237, v31, v23, s[44:45]
	v_cndmask_b32_e64 v234, v19, v31, s[36:37]
	v_cndmask_b32_e64 v238, v19, v31, s[44:45]
	v_cndmask_b32_e64 v235, v27, v19, s[36:37]
	v_cndmask_b32_e64 v239, v27, v19, s[44:45]
	v_fma_f32 v206, v78, v22, v70
	v_fma_f32 v229, v78, v30, v70
	v_fma_f32 v230, v78, v18, v70
	v_fma_f32 v231, v78, v26, v70
	v_fma_f32 v207, v79, v23, v71
	v_fma_f32 v196, v79, v31, v71
	v_fma_f32 v197, v79, v19, v71
	v_fma_f32 v176, v79, v27, v71
	v_fmac_f32_dpp v206, v221, v74 row_ror:1 row_mask:0xf bank_mask:0xf
	v_fmac_f32_dpp v229, v222, v74 row_ror:1 row_mask:0xf bank_mask:0xf
	v_fmac_f32_dpp v230, v223, v74 row_ror:1 row_mask:0xf bank_mask:0xf
	v_fmac_f32_dpp v231, v224, v74 row_ror:1 row_mask:0xf bank_mask:0xf
	v_fmac_f32_dpp v207, v232, v75 row_ror:1 row_mask:0xf bank_mask:0xf
	v_fmac_f32_dpp v196, v233, v75 row_ror:1 row_mask:0xf bank_mask:0xf
	v_fmac_f32_dpp v197, v234, v75 row_ror:1 row_mask:0xf bank_mask:0xf
	v_fmac_f32_dpp v176, v235, v75 row_ror:1 row_mask:0xf bank_mask:0xf
	v_fmac_f32_dpp v206, v225, v66 row_ror:2 row_mask:0xf bank_mask:0xf
	v_fmac_f32_dpp v229, v226, v66 row_ror:2 row_mask:0xf bank_mask:0xf
	v_fmac_f32_dpp v230, v227, v66 row_ror:2 row_mask:0xf bank_mask:0xf
	v_fmac_f32_dpp v231, v228, v66 row_ror:2 row_mask:0xf bank_mask:0xf
	v_fmac_f32_dpp v207, v236, v67 row_ror:2 row_mask:0xf bank_mask:0xf
	v_fmac_f32_dpp v196, v237, v67 row_ror:2 row_mask:0xf bank_mask:0xf
	v_fmac_f32_dpp v197, v238, v67 row_ror:2 row_mask:0xf bank_mask:0xf
	v_fmac_f32_dpp v176, v239, v67 row_ror:2 row_mask:0xf bank_mask:0xf
	v_exp_f32_e32 v221, v206
	v_exp_f32_e32 v222, v229
	v_exp_f32_e32 v223, v230
	v_exp_f32_e32 v224, v231
	v_exp_f32_e32 v232, v207
	v_exp_f32_e32 v233, v196
	v_exp_f32_e32 v234, v197
	v_exp_f32_e32 v235, v176
	v_fma_f32 v221, v221, v169, v169
	v_fma_f32 v222, v222, v177, v177
	v_fma_f32 v223, v223, v191, v191
	v_fma_f32 v224, v224, v199, v199
	v_fma_f32 v232, v232, v169, v169
	v_fma_f32 v233, v233, v177, v177
	v_fma_f32 v234, v234, v191, v191
	v_fma_f32 v235, v235, v199, v199
	v_rcp_f32_e32 v221, v221
	v_rcp_f32_e32 v222, v222
	v_rcp_f32_e32 v223, v223
	v_rcp_f32_e32 v224, v224
	v_rcp_f32_e32 v232, v232
	v_rcp_f32_e32 v233, v233
	v_rcp_f32_e32 v234, v234
	v_rcp_f32_e32 v235, v235
	v_mul_f32_e32 v221, v206, v221
	v_mul_f32_e32 v222, v229, v222
	v_mul_f32_e32 v223, v230, v223
	v_mul_f32_e32 v224, v231, v224
	v_mul_f32_e32 v232, v207, v232
	v_mul_f32_e32 v233, v196, v233
	v_mul_f32_e32 v234, v197, v234
	v_mul_f32_e32 v235, v176, v235
	v_mul_f32_e32 v242, v14, v248
	v_mul_f32_e32 v243, v15, v248
	v_mul_f32_e32 v14, v221, v14
	v_mul_f32_e32 v10, v222, v10
	v_mul_f32_e32 v6, v223, v6
	v_mul_f32_e32 v2, v224, v2
	v_mul_f32_e32 v15, v232, v15
	v_mul_f32_e32 v11, v233, v11
	v_mul_f32_e32 v7, v234, v7
	v_mul_f32_e32 v3, v235, v3
	v_cvt_pk_bf16_f32 v44, v44, v45
	v_cvt_pk_bf16_f32 v45, v46, v47
	v_cvt_pk_bf16_f32 v46, v12, v13
	v_cvt_pk_bf16_f32 v47, v14, v15
	v_cvt_pk_bf16_f32 v40, v40, v41
	v_cvt_pk_bf16_f32 v41, v42, v43
	v_cvt_pk_bf16_f32 v42, v8, v9
	v_cvt_pk_bf16_f32 v43, v10, v11
	v_cvt_pk_bf16_f32 v36, v36, v37
	v_cvt_pk_bf16_f32 v37, v38, v39
	v_cvt_pk_bf16_f32 v38, v4, v5
	v_cvt_pk_bf16_f32 v39, v6, v7
	v_cvt_pk_bf16_f32 v32, v32, v33
	v_cvt_pk_bf16_f32 v33, v34, v35
	v_cvt_pk_bf16_f32 v34, v0, v1
	v_cvt_pk_bf16_f32 v35, v2, v3
	v_mul_f32_e32 v200, 0xbf317218, v200
	v_mul_f32_e32 v201, 0xbf317218, v201
	v_mul_f32_e32 v202, 0xbf317218, v202
	v_mul_f32_e32 v203, 0xbf317218, v203
	v_mul_f32_e32 v204, 0xbf317218, v204
	v_mul_f32_e32 v205, 0xbf317218, v205
	v_mul_f32_e32 v206, 0xbf317218, v206
	v_mul_f32_e32 v207, 0xbf317218, v207
	v_or_b32_e32 v170, s11, v216
	v_mul_u32_u24_e32 v170, s10, v170
	v_lshl_add_u32 v170, v170, 2, v190
	s_and_saveexec_b64 s[0:1], s[42:43]
	global_store_dwordx4 v170, v[200:203], s[50:51]
	global_store_dwordx4 v170, v[204:207], s[50:51] offset:16
	global_store_dwordx4 v170, v[192:195], s[92:93]
	global_store_dwordx4 v170, v[240:243], s[92:93] offset:16
	s_or_b64 exec, exec, s[0:1]
	v_add_u32_e32 v171, s11, v218
	v_mul_u32_u24_e32 v171, s10, v171
	v_lshl_add_u32 v171, v171, 2, v190
	s_and_saveexec_b64 s[0:1], s[44:45]
	global_store_dwordx4 v171, v[52:55], s[52:53]
	global_store_dwordx4 v171, v[24:27], s[52:53] offset:16
	s_or_b64 exec, exec, s[0:1]
	v_mad_u32_u24 v172, v168, s20, v189
	s_and_saveexec_b64 s[0:1], s[40:41]
	global_store_dwordx4 v172, v[44:47], s[94:95]
	s_or_b64 exec, exec, s[0:1]
	v_add_u32_e32 v172, 0x16000, v172
	global_store_dwordx4 v172, v[40:43], s[94:95]
	v_add_u32_e32 v172, 0x16000, v172
	global_store_dwordx4 v172, v[36:39], s[94:95]
	v_add_u32_e32 v172, 0x16000, v172
	global_store_dwordx4 v172, v[32:35], s[94:95]
	s_and_b64 vcc, exec, s[46:47]
	s_mov_b32 s0, s76
	s_mov_b32 s84, s78
	s_mov_b64 s[82:83], s[72:73]
	s_mov_b64 s[86:87], s[80:81]
	s_cbranch_vccnz .LBB0_146
	s_branch .LBB0_122
